# P2 Q-section: q_norm_g and sink loads batched with the Q loads (one vmcnt wait instead of ten)
# speedup vs baseline: 1.0013x; 1.0013x over previous
; __device__ __forceinline__ unsigned cvt_pk_bf16(float lo, float hi) { unsigned r; asm volatile("v_cvt_pk_bf16_f32 %0, %1, %2" : "=v"(r) : "v"(lo), "v"(hi)); return r; }
; __device__ __forceinline__ float bf_lo(unsigned w) { return __uint_as_float(w << 16); }
; __device__ __forceinline__ float bf_hi(unsigned w) { return __uint_as_float(w & 0xffff0000u); }
; __device__ __forceinline__ float x32_sum(float x) { auto s = __builtin_amdgcn_permlane32_swap(__float_as_uint(x), __float_as_uint(x), false, false); return __uint_as_float(s[0]) + __uint_as_float(s[1]); }
; __device__ __forceinline__ void p2_phase(LAS unsigned char* lds, const Args& a, int vcu, int G, bf16_t* Mout) {
;     ...
;             const char* qb = (const char*)(Qg + (size_t)(tok0 + 32 * qt) * DM + hd * 128); u32x4 raw[8]; float ss = 0.f;
; #pragma unroll
;             for (int s = 0; s < 8; ++s) raw[s] = ldg16(qb + 32 * s, offQ);
; #pragma unroll
;             for (int s = 0; s < 8; ++s)
; #pragma unroll
;                 for (int e = 0; e < 4; ++e) { const float lo = bf_lo(raw[s][e]), hi = bf_hi(raw[s][e]); ss += lo * lo + hi * hi; }
;             ss = x32_sum(ss);
;             const float sc = __builtin_amdgcn_rsqf(ss * (1.0f / 128.0f) + EPS) * (0.08838834764831845f * LOG2E);
;             const float* qg = a.in[I_QG] + 8 * h;
; #pragma unroll
;             for (int s = 0; s < 8; ++s) { const f32x4 g0 = *(const f32x4*)(qg + 16 * s), g1 = *(const f32x4*)(qg + 16 * s + 4); u32x4 w;
;                 w.x = cvt_pk_bf16(bf_lo(raw[s][0]) * sc * g0[0], bf_hi(raw[s][0]) * sc * g0[1]); w.y = cvt_pk_bf16(bf_lo(raw[s][1]) * sc * g0[2], bf_hi(raw[s][1]) * sc * g0[3]);
;                 w.z = cvt_pk_bf16(bf_lo(raw[s][2]) * sc * g1[0], bf_hi(raw[s][2]) * sc * g1[1]); w.w = cvt_pk_bf16(bf_lo(raw[s][3]) * sc * g1[2], bf_hi(raw[s][3]) * sc * g1[3]);
;                 Qf[s] = __builtin_bit_cast(bf16x8, w); }
;             m_run = a.in[I_SINK][hd] * LOG2E; l_run = (h == 0) ? 1.0f : 0.0f;
.LBB0_267:
	s_lshl_b32 s4, s74, 1
	s_add_i32 s4, s4, s49
	s_lshl_b32 s42, s4, 8
	s_mov_b32 s43, s23
	v_lshl_add_u64 v[2:3], v[188:189], 0, s[42:43]
	global_load_dwordx4 v[18:21], v[2:3], off
	global_load_dwordx4 v[22:25], v[2:3], off offset:32
	global_load_dwordx4 v[26:29], v[2:3], off offset:64
	global_load_dwordx4 v[30:33], v[2:3], off offset:96
	global_load_dwordx4 v[14:17], v[2:3], off offset:128
	global_load_dwordx4 v[10:13], v[2:3], off offset:160
	global_load_dwordx4 v[6:9], v[2:3], off offset:192
	s_nop 0
	global_load_dwordx4 v[2:5], v[2:3], off offset:224
	s_mov_b32 s5, s23
	s_lshl_b32 s22, s4, 7
	s_lshl_b64 s[4:5], s[4:5], 2
	s_add_u32 s4, s16, s4
	s_addc_u32 s5, s17, s5
	s_add_i32 s73, s74, 1
	v_mov_b32_e32 v237, v236
	v_mov_b32_e32 v238, v218
	global_load_dwordx4 v[150:153], v[182:183], off offset:16
	global_load_dwordx4 v[146:149], v[182:183], off
	global_load_dwordx4 v[138:141], v[182:183], off offset:64
	global_load_dwordx4 v[142:145], v[182:183], off offset:80
	global_load_dwordx4 v[154:157], v[182:183], off offset:128
	global_load_dwordx4 v[158:161], v[182:183], off offset:144
	global_load_dwordx4 v[162:165], v[182:183], off offset:192
	global_load_dwordx4 v[166:169], v[182:183], off offset:208
	global_load_dwordx4 v[192:195], v[182:183], off offset:256
	global_load_dwordx4 v[196:199], v[182:183], off offset:272
	global_load_dwordx4 v[200:203], v[182:183], off offset:320
	global_load_dwordx4 v[204:207], v[182:183], off offset:336
	global_load_dwordx4 v[240:243], v[182:183], off offset:384
	global_load_dwordx4 v[244:247], v[182:183], off offset:400
	global_load_dwordx4 v[248:251], v[182:183], off offset:448
	global_load_dwordx4 v[252:255], v[182:183], off offset:464
	global_load_dword v239, v0, s[4:5]
	s_waitcnt vmcnt(0)
	v_and_b32_e32 v34, 0xffff0000, v18
	v_and_b32_e32 v36, 0xffff0000, v19
	v_lshlrev_b32_e32 v1, 16, v18
	v_lshlrev_b32_e32 v35, 16, v19
	v_and_b32_e32 v38, 0xffff0000, v20
	v_mul_f32_e32 v18, v34, v34
	v_mul_f32_e32 v19, v36, v36
	v_lshlrev_b32_e32 v37, 16, v20
	v_and_b32_e32 v40, 0xffff0000, v21
	v_mul_f32_e32 v20, v38, v38
	v_fmac_f32_e32 v18, v1, v1
	v_fmac_f32_e32 v19, v35, v35
	v_lshlrev_b32_e32 v39, 16, v21
	v_and_b32_e32 v42, 0xffff0000, v22
	v_mul_f32_e32 v21, v40, v40
	v_fmac_f32_e32 v20, v37, v37
	v_add_f32_e32 v18, v18, v19
	v_lshlrev_b32_e32 v41, 16, v22
	v_and_b32_e32 v44, 0xffff0000, v23
	v_mul_f32_e32 v22, v42, v42
	v_fmac_f32_e32 v21, v39, v39
	v_add_f32_e32 v18, v20, v18
	v_lshlrev_b32_e32 v43, 16, v23
	v_and_b32_e32 v46, 0xffff0000, v24
	v_mul_f32_e32 v23, v44, v44
	v_fmac_f32_e32 v22, v41, v41
	v_add_f32_e32 v18, v21, v18
	v_lshlrev_b32_e32 v45, 16, v24
	v_and_b32_e32 v48, 0xffff0000, v25
	v_mul_f32_e32 v24, v46, v46
	v_fmac_f32_e32 v23, v43, v43
	v_add_f32_e32 v18, v22, v18
	v_lshlrev_b32_e32 v47, 16, v25
	v_lshlrev_b32_e32 v49, 16, v26
	v_and_b32_e32 v26, 0xffff0000, v26
	v_mul_f32_e32 v25, v48, v48
	v_fmac_f32_e32 v24, v45, v45
	v_add_f32_e32 v18, v23, v18
	v_lshlrev_b32_e32 v50, 16, v27
	v_and_b32_e32 v27, 0xffff0000, v27
	v_mul_f32_e32 v60, v26, v26
	v_fmac_f32_e32 v25, v47, v47
	v_add_f32_e32 v18, v24, v18
	v_lshlrev_b32_e32 v51, 16, v28
	v_and_b32_e32 v28, 0xffff0000, v28
	v_mul_f32_e32 v61, v27, v27
	v_fmac_f32_e32 v60, v49, v49
	v_add_f32_e32 v18, v25, v18
	v_lshlrev_b32_e32 v52, 16, v29
	v_and_b32_e32 v29, 0xffff0000, v29
	v_mul_f32_e32 v62, v28, v28
	v_fmac_f32_e32 v61, v50, v50
	v_add_f32_e32 v18, v60, v18
	v_lshlrev_b32_e32 v53, 16, v30
	v_and_b32_e32 v30, 0xffff0000, v30
	v_mul_f32_e32 v63, v29, v29
	v_fmac_f32_e32 v62, v51, v51
	v_add_f32_e32 v18, v61, v18
	v_lshlrev_b32_e32 v54, 16, v31
	v_and_b32_e32 v31, 0xffff0000, v31
	v_mul_f32_e32 v64, v30, v30
	v_fmac_f32_e32 v63, v52, v52
	v_add_f32_e32 v18, v62, v18
	v_lshlrev_b32_e32 v55, 16, v32
	v_and_b32_e32 v32, 0xffff0000, v32
	v_mul_f32_e32 v65, v31, v31
	v_fmac_f32_e32 v64, v53, v53
	v_add_f32_e32 v18, v63, v18
	v_lshlrev_b32_e32 v56, 16, v33
	v_and_b32_e32 v33, 0xffff0000, v33
	v_mul_f32_e32 v66, v32, v32
	v_fmac_f32_e32 v65, v54, v54
	v_add_f32_e32 v18, v64, v18
	v_lshlrev_b32_e32 v57, 16, v14
	v_and_b32_e32 v14, 0xffff0000, v14
	v_mul_f32_e32 v67, v33, v33
	v_fmac_f32_e32 v66, v55, v55
	v_add_f32_e32 v18, v65, v18
	v_lshlrev_b32_e32 v58, 16, v15
	v_and_b32_e32 v15, 0xffff0000, v15
	v_mul_f32_e32 v68, v14, v14
	v_fmac_f32_e32 v67, v56, v56
	v_add_f32_e32 v18, v66, v18
	v_mul_f32_e32 v69, v15, v15
	v_fmac_f32_e32 v68, v57, v57
	v_add_f32_e32 v18, v67, v18
	v_fmac_f32_e32 v69, v58, v58
	v_add_f32_e32 v18, v68, v18
	v_add_f32_e32 v60, v69, v18
	v_lshlrev_b32_e32 v59, 16, v16
	v_and_b32_e32 v16, 0xffff0000, v16
	v_mul_f32_e32 v61, v16, v16
	v_fmac_f32_e32 v61, v59, v59
	v_add_f32_e32 v60, v61, v60
	v_lshlrev_b32_e32 v61, 16, v17
	v_and_b32_e32 v17, 0xffff0000, v17
	v_mul_f32_e32 v62, v17, v17
	v_fmac_f32_e32 v62, v61, v61
	v_add_f32_e32 v60, v62, v60
	v_lshlrev_b32_e32 v62, 16, v10
	v_and_b32_e32 v10, 0xffff0000, v10
	v_mul_f32_e32 v63, v10, v10
	v_fmac_f32_e32 v63, v62, v62
	v_add_f32_e32 v60, v63, v60
	v_lshlrev_b32_e32 v63, 16, v11
	v_and_b32_e32 v11, 0xffff0000, v11
	v_mul_f32_e32 v64, v11, v11
	v_fmac_f32_e32 v64, v63, v63
	v_add_f32_e32 v60, v64, v60
	v_lshlrev_b32_e32 v64, 16, v12
	v_and_b32_e32 v12, 0xffff0000, v12
	v_mul_f32_e32 v65, v12, v12
	v_fmac_f32_e32 v65, v64, v64
	v_add_f32_e32 v60, v65, v60
	v_lshlrev_b32_e32 v65, 16, v13
	v_and_b32_e32 v13, 0xffff0000, v13
	v_mul_f32_e32 v66, v13, v13
	v_fmac_f32_e32 v66, v65, v65
	v_and_b32_e32 v67, 0xffff0000, v6
	v_add_f32_e32 v60, v66, v60
	v_lshlrev_b32_e32 v66, 16, v6
	v_mul_f32_e32 v6, v67, v67
	v_fmac_f32_e32 v6, v66, v66
	v_and_b32_e32 v68, 0xffff0000, v7
; __device__ __forceinline__ unsigned cvt_pk_bf16(float lo, float hi) { unsigned r; asm volatile("v_cvt_pk_bf16_f32 %0, %1, %2" : "=v"(r) : "v"(lo), "v"(hi)); return r; }
; __device__ __forceinline__ float bf_lo(unsigned w) { return __uint_as_float(w << 16); }
; __device__ __forceinline__ float bf_hi(unsigned w) { return __uint_as_float(w & 0xffff0000u); }
; __device__ __forceinline__ float x32_sum(float x) { auto s = __builtin_amdgcn_permlane32_swap(__float_as_uint(x), __float_as_uint(x), false, false); return __uint_as_float(s[0]) + __uint_as_float(s[1]); }
; __device__ __forceinline__ void p2_phase(LAS unsigned char* lds, const Args& a, int vcu, int G, bf16_t* Mout) {
;     ...
;                 for (int e = 0; e < 4; ++e) { const float lo = bf_lo(raw[s][e]), hi = bf_hi(raw[s][e]); ss += lo * lo + hi * hi; }
;             ss = x32_sum(ss);
;             const float sc = __builtin_amdgcn_rsqf(ss * (1.0f / 128.0f) + EPS) * (0.08838834764831845f * LOG2E);
;             const float* qg = a.in[I_QG] + 8 * h;
; #pragma unroll
;             for (int s = 0; s < 8; ++s) { const f32x4 g0 = *(const f32x4*)(qg + 16 * s), g1 = *(const f32x4*)(qg + 16 * s + 4); u32x4 w;
;                 w.x = cvt_pk_bf16(bf_lo(raw[s][0]) * sc * g0[0], bf_hi(raw[s][0]) * sc * g0[1]); w.y = cvt_pk_bf16(bf_lo(raw[s][1]) * sc * g0[2], bf_hi(raw[s][1]) * sc * g0[3]);
;                 w.z = cvt_pk_bf16(bf_lo(raw[s][2]) * sc * g1[0], bf_hi(raw[s][2]) * sc * g1[1]); w.w = cvt_pk_bf16(bf_lo(raw[s][3]) * sc * g1[2], bf_hi(raw[s][3]) * sc * g1[3]);
;                 Qf[s] = __builtin_bit_cast(bf16x8, w); }
	v_add_f32_e32 v6, v6, v60
	v_lshlrev_b32_e32 v60, 16, v7
	v_mul_f32_e32 v7, v68, v68
	v_fmac_f32_e32 v7, v60, v60
	v_and_b32_e32 v70, 0xffff0000, v8
	v_add_f32_e32 v6, v7, v6
	v_lshlrev_b32_e32 v69, 16, v8
	v_mul_f32_e32 v7, v70, v70
	v_fmac_f32_e32 v7, v69, v69
	v_and_b32_e32 v72, 0xffff0000, v9
	v_add_f32_e32 v6, v7, v6
	v_lshlrev_b32_e32 v71, 16, v9
	v_mul_f32_e32 v7, v72, v72
	v_and_b32_e32 v74, 0xffff0000, v2
	v_fmac_f32_e32 v7, v71, v71
	v_lshlrev_b32_e32 v73, 16, v2
	v_mul_f32_e32 v2, v74, v74
	v_and_b32_e32 v76, 0xffff0000, v3
	v_add_f32_e32 v6, v7, v6
	v_fmac_f32_e32 v2, v73, v73
	v_lshlrev_b32_e32 v75, 16, v3
	v_mul_f32_e32 v3, v76, v76
	v_add_f32_e32 v2, v2, v6
	v_fmac_f32_e32 v3, v75, v75
	v_and_b32_e32 v78, 0xffff0000, v4
	v_add_f32_e32 v2, v3, v2
	v_lshlrev_b32_e32 v77, 16, v4
	v_mul_f32_e32 v3, v78, v78
	v_fmac_f32_e32 v3, v77, v77
	v_and_b32_e32 v80, 0xffff0000, v5
	v_add_f32_e32 v2, v3, v2
	v_lshlrev_b32_e32 v79, 16, v5
	v_mul_f32_e32 v3, v80, v80
	v_fmac_f32_e32 v3, v79, v79
	v_add_f32_e32 v2, v3, v2
	v_mov_b32_e32 v3, v2
	s_nop 1
	v_permlane32_swap_b32_e32 v2, v3
	v_add_f32_e32 v2, v2, v3
	v_fmamk_f32 v2, v2, 0x3c000000, v228
	v_rsq_f32_e32 v2, v2
	s_nop 0
	v_mul_f32_e32 v81, 0x3e0293ee, v2
	v_mul_f32_e32 v2, v81, v34
	v_mul_f32_e32 v1, v81, v1
	v_mul_f32_e32 v2, v147, v2
	v_mul_f32_e32 v1, v146, v1
	v_cvt_pk_bf16_f32 v122, v1, v2
	v_mul_f32_e32 v2, v81, v36
	v_mul_f32_e32 v1, v81, v35
	v_mul_f32_e32 v2, v149, v2
	v_mul_f32_e32 v1, v148, v1
	v_cvt_pk_bf16_f32 v123, v1, v2
	v_mul_f32_e32 v2, v81, v38
	v_mul_f32_e32 v1, v81, v37
	v_mul_f32_e32 v2, v151, v2
	v_mul_f32_e32 v1, v150, v1
	v_cvt_pk_bf16_f32 v124, v1, v2
	v_mul_f32_e32 v2, v81, v40
	v_mul_f32_e32 v1, v81, v39
	v_mul_f32_e32 v2, v153, v2
	v_mul_f32_e32 v1, v152, v1
	v_cvt_pk_bf16_f32 v125, v1, v2
	v_mul_f32_e32 v1, v81, v41
	v_mul_f32_e32 v18, v81, v42
	v_mul_f32_e32 v20, v81, v44
	v_mul_f32_e32 v19, v81, v43
	v_mul_f32_e32 v21, v81, v51
	v_mul_f32_e32 v22, v81, v28
	v_mul_f32_e32 v23, v81, v52
	v_mul_f32_e32 v24, v81, v29
	v_mul_f32_e32 v14, v81, v14
	v_mul_f32_e32 v15, v81, v15
	v_mul_f32_e32 v16, v81, v16
	v_mul_f32_e32 v17, v81, v17
	v_mul_f32_e32 v10, v81, v10
	v_mul_f32_e32 v11, v81, v11
	v_mul_f32_e32 v12, v81, v12
	v_mul_f32_e32 v13, v81, v13
	v_mul_f32_e32 v1, v138, v1
	v_mul_f32_e32 v2, v139, v18
	v_cvt_pk_bf16_f32 v126, v1, v2
	v_mul_f32_e32 v1, v141, v20
	v_mul_f32_e32 v2, v81, v46
	v_mul_f32_e32 v3, v140, v19
	v_cvt_pk_bf16_f32 v127, v3, v1
	v_mul_f32_e32 v1, v81, v45
	v_mul_f32_e32 v2, v2, v143
	v_mul_f32_e32 v1, v1, v142
	v_cvt_pk_bf16_f32 v128, v1, v2
	v_mul_f32_e32 v2, v81, v48
	v_mul_f32_e32 v1, v81, v47
	v_mul_f32_e32 v2, v2, v145
	v_mul_f32_e32 v1, v1, v144
	v_cvt_pk_bf16_f32 v129, v1, v2
	v_mul_f32_e32 v1, v81, v49
	v_mul_f32_e32 v18, v81, v26
	v_mul_f32_e32 v19, v81, v50
	v_mul_f32_e32 v20, v81, v27
	v_mul_f32_e32 v1, v1, v154
	v_mul_f32_e32 v2, v18, v155
	v_mul_f32_e32 v3, v19, v156
	v_mul_f32_e32 v4, v20, v157
	v_mul_f32_e32 v5, v21, v158
	v_mul_f32_e32 v6, v22, v159
	v_mul_f32_e32 v7, v23, v160
	v_mul_f32_e32 v8, v24, v161
	v_cvt_pk_bf16_f32 v130, v1, v2
	v_cvt_pk_bf16_f32 v131, v3, v4
	v_cvt_pk_bf16_f32 v132, v5, v6
	v_cvt_pk_bf16_f32 v133, v7, v8
	v_mul_f32_e32 v1, v81, v53
	v_mul_f32_e32 v18, v81, v30
	v_mul_f32_e32 v19, v81, v54
	v_mul_f32_e32 v20, v81, v31
	v_mul_f32_e32 v21, v81, v55
	v_mul_f32_e32 v22, v81, v32
	v_mul_f32_e32 v23, v81, v56
	v_mul_f32_e32 v24, v81, v33
	v_mul_f32_e32 v1, v1, v162
	v_mul_f32_e32 v2, v18, v163
	v_mul_f32_e32 v3, v19, v164
	v_mul_f32_e32 v4, v20, v165
	v_mul_f32_e32 v5, v21, v166
	v_mul_f32_e32 v6, v22, v167
	v_mul_f32_e32 v7, v23, v168
	v_mul_f32_e32 v8, v24, v169
	v_cvt_pk_bf16_f32 v134, v1, v2
	v_cvt_pk_bf16_f32 v135, v3, v4
	v_cvt_pk_bf16_f32 v136, v5, v6
	v_cvt_pk_bf16_f32 v137, v7, v8
	v_mul_f32_e32 v1, v81, v57
	v_mul_f32_e32 v18, v81, v58
	v_mul_f32_e32 v19, v81, v59
	v_mul_f32_e32 v20, v81, v61
	v_mul_f32_e32 v1, v1, v192
	v_mul_f32_e32 v2, v14, v193
	v_mul_f32_e32 v3, v18, v194
	v_mul_f32_e32 v4, v15, v195
	v_mul_f32_e32 v5, v19, v196
	v_mul_f32_e32 v6, v16, v197
; __device__ __forceinline__ unsigned cvt_pk_bf16(float lo, float hi) { unsigned r; asm volatile("v_cvt_pk_bf16_f32 %0, %1, %2" : "=v"(r) : "v"(lo), "v"(hi)); return r; }
; __device__ __forceinline__ float bf_lo(unsigned w) { return __uint_as_float(w << 16); }
; __device__ __forceinline__ float bf_hi(unsigned w) { return __uint_as_float(w & 0xffff0000u); }
; __device__ __forceinline__ void p2_phase(LAS unsigned char* lds, const Args& a, int vcu, int G, bf16_t* Mout) {
;     ...
;             for (int s = 0; s < 8; ++s) { const f32x4 g0 = *(const f32x4*)(qg + 16 * s), g1 = *(const f32x4*)(qg + 16 * s + 4); u32x4 w;
;                 w.x = cvt_pk_bf16(bf_lo(raw[s][0]) * sc * g0[0], bf_hi(raw[s][0]) * sc * g0[1]); w.y = cvt_pk_bf16(bf_lo(raw[s][1]) * sc * g0[2], bf_hi(raw[s][1]) * sc * g0[3]);
;                 w.z = cvt_pk_bf16(bf_lo(raw[s][2]) * sc * g1[0], bf_hi(raw[s][2]) * sc * g1[1]); w.w = cvt_pk_bf16(bf_lo(raw[s][3]) * sc * g1[2], bf_hi(raw[s][3]) * sc * g1[3]);
;                 Qf[s] = __builtin_bit_cast(bf16x8, w); }
;             m_run = a.in[I_SINK][hd] * LOG2E; l_run = (h == 0) ? 1.0f : 0.0f;
; #pragma unroll
;             for (int dt = 0; dt < 4; ++dt)
; #pragma unroll
;                 for (int i = 0; i < 16; ++i) O[dt][i] = 0.f;
;         }
;         for (int kb = kb_lo; kb <= kb_hi; ++kb) {
	v_mul_f32_e32 v7, v20, v198
	v_mul_f32_e32 v8, v17, v199
	v_cvt_pk_bf16_f32 v138, v1, v2
	v_cvt_pk_bf16_f32 v139, v3, v4
	v_cvt_pk_bf16_f32 v140, v5, v6
	v_cvt_pk_bf16_f32 v141, v7, v8
	v_mul_f32_e32 v1, v81, v62
	v_mul_f32_e32 v14, v81, v63
	v_mul_f32_e32 v15, v81, v64
	v_mul_f32_e32 v16, v81, v65
	v_mul_f32_e32 v1, v1, v200
	v_mul_f32_e32 v2, v10, v201
	v_mul_f32_e32 v3, v14, v202
	v_mul_f32_e32 v4, v11, v203
	v_mul_f32_e32 v5, v15, v204
	v_mul_f32_e32 v6, v12, v205
	v_mul_f32_e32 v7, v16, v206
	v_mul_f32_e32 v8, v13, v207
	v_cvt_pk_bf16_f32 v142, v1, v2
	v_cvt_pk_bf16_f32 v143, v3, v4
	v_cvt_pk_bf16_f32 v144, v5, v6
	v_cvt_pk_bf16_f32 v145, v7, v8
	v_mul_f32_e32 v1, v81, v66
	v_mul_f32_e32 v10, v81, v67
	v_mul_f32_e32 v11, v81, v60
	v_mul_f32_e32 v12, v81, v68
	v_mul_f32_e32 v13, v81, v69
	v_mul_f32_e32 v14, v81, v70
	v_mul_f32_e32 v15, v81, v71
	v_mul_f32_e32 v16, v81, v72
	v_mul_f32_e32 v1, v1, v240
	v_mul_f32_e32 v2, v10, v241
	v_mul_f32_e32 v3, v11, v242
	v_mul_f32_e32 v4, v12, v243
	v_mul_f32_e32 v5, v13, v244
	v_mul_f32_e32 v6, v14, v245
	v_mul_f32_e32 v7, v15, v246
	v_mul_f32_e32 v8, v16, v247
	v_cvt_pk_bf16_f32 v146, v1, v2
	v_cvt_pk_bf16_f32 v147, v3, v4
	v_cvt_pk_bf16_f32 v148, v5, v6
	v_cvt_pk_bf16_f32 v149, v7, v8
	v_mul_f32_e32 v1, v81, v73
	v_mul_f32_e32 v10, v81, v74
	v_mul_f32_e32 v11, v81, v75
	v_mul_f32_e32 v12, v81, v76
	v_mul_f32_e32 v13, v81, v77
	v_mul_f32_e32 v14, v81, v78
	v_mul_f32_e32 v15, v81, v79
	v_mul_f32_e32 v16, v81, v80
	v_mul_f32_e32 v1, v1, v248
	v_mul_f32_e32 v2, v10, v249
	v_mul_f32_e32 v3, v11, v250
	v_mul_f32_e32 v4, v12, v251
	v_mul_f32_e32 v5, v13, v252
	v_mul_f32_e32 v6, v14, v253
	v_mul_f32_e32 v7, v15, v254
	v_mul_f32_e32 v8, v16, v255
	v_cvt_pk_bf16_f32 v150, v1, v2
	v_cvt_pk_bf16_f32 v151, v3, v4
	v_cvt_pk_bf16_f32 v152, v5, v6
	v_cvt_pk_bf16_f32 v153, v7, v8
	s_lshl_b32 s4, s74, 8
	v_mov_b32_e32 v14, v0
	v_mov_b32_e32 v15, v0
	s_add_i32 s75, s4, s45
	v_mov_b32_e32 v1, v0
	v_mov_b32_e32 v2, v0
	v_mov_b32_e32 v3, v0
	v_mov_b32_e32 v4, v0
	v_mov_b32_e32 v5, v0
	v_mov_b32_e32 v6, v0
	v_mov_b32_e32 v7, v0
	v_mov_b32_e32 v8, v0
	v_mov_b32_e32 v9, v0
	v_mov_b32_e32 v10, v0
	v_mov_b32_e32 v11, v0
	v_mov_b32_e32 v12, v0
	v_mov_b32_e32 v13, v0
	v_mov_b64_e32 v[64:65], v[14:15]
	v_mov_b64_e32 v[48:49], v[14:15]
	v_mov_b64_e32 v[32:33], v[14:15]
	s_cmp_eq_u32 s73, 4
	v_mad_u64_u32 v[192:193], s[4:5], s75, v233, v[190:191]
	v_mov_b64_e32 v[62:63], v[12:13]
	v_mov_b64_e32 v[60:61], v[10:11]
	v_mov_b64_e32 v[58:59], v[8:9]
	v_mov_b64_e32 v[56:57], v[6:7]
	v_mov_b64_e32 v[54:55], v[4:5]
	v_mov_b64_e32 v[52:53], v[2:3]
	v_mov_b64_e32 v[50:51], v[0:1]
	v_mov_b64_e32 v[46:47], v[12:13]
	v_mov_b64_e32 v[44:45], v[10:11]
	v_mov_b64_e32 v[42:43], v[8:9]
	v_mov_b64_e32 v[40:41], v[6:7]
	v_mov_b64_e32 v[38:39], v[4:5]
	v_mov_b64_e32 v[36:37], v[2:3]
	v_mov_b64_e32 v[34:35], v[0:1]
	v_mov_b64_e32 v[30:31], v[12:13]
	v_mov_b64_e32 v[28:29], v[10:11]
	v_mov_b64_e32 v[26:27], v[8:9]
	v_mov_b64_e32 v[24:25], v[6:7]
	v_mov_b64_e32 v[22:23], v[4:5]
	v_mov_b64_e32 v[20:21], v[2:3]
	v_mov_b64_e32 v[18:19], v[0:1]
	v_mov_b64_e32 v[16:17], v[14:15]
	s_cselect_b64 s[42:43], -1, 0
	s_add_i32 s4, s75, 32
	s_add_i32 s76, s75, 64
	s_add_i32 s77, s75, 0x60
	s_add_i32 s78, s75, 0x80
	s_add_i32 s79, s75, 0xa0
	s_add_i32 s80, s75, 0xc0
	s_addk_i32 s75, 0xe0
	v_mov_b64_e32 v[14:15], v[12:13]
	v_mov_b64_e32 v[12:13], v[10:11]
	v_mov_b64_e32 v[10:11], v[8:9]
	v_mov_b64_e32 v[8:9], v[6:7]
	v_mov_b64_e32 v[6:7], v[4:5]
	v_mov_b64_e32 v[4:5], v[2:3]
	v_mov_b64_e32 v[2:3], v[0:1]
	v_mad_u64_u32 v[194:195], s[4:5], s4, v233, v[190:191]
	v_mad_u64_u32 v[196:197], s[4:5], s76, v233, v[190:191]
	v_mad_u64_u32 v[198:199], s[4:5], s77, v233, v[190:191]
	v_mad_u64_u32 v[200:201], s[4:5], s78, v233, v[190:191]
	v_mad_u64_u32 v[202:203], s[4:5], s79, v233, v[190:191]
	v_mad_u64_u32 v[204:205], s[4:5], s80, v233, v[190:191]
	v_mad_u64_u32 v[206:207], s[4:5], s75, v233, v[190:191]
	s_mov_b32 s76, s70
	v_mul_f32_e32 v1, 0x3fb8aa3b, v239
	v_cmp_ne_u32_e32 vcc, s76, v235
	s_cbranch_vccnz .LBB0_269

; #define LAS __attribute__((address_space(3)))
; __global__ void __launch_bounds__(512, 2) fwd_megakernel(Args a) {
;     extern __shared__ __attribute__((aligned(16))) unsigned char shm[];
;     LAS unsigned char* lds = (LAS unsigned char*)shm;
;     const int tid = threadIdx.x, lane = tid & 63, wave = __builtin_amdgcn_readfirstlane(tid >> 6);
	.amdhsa_kernel _Z14fwd_megakernel4Args
		.amdhsa_group_segment_fixed_size 0
		.amdhsa_private_segment_fixed_size 0
		.amdhsa_kernarg_size 400
		.amdhsa_user_sgpr_count 2
		.amdhsa_user_sgpr_dispatch_ptr 0
		.amdhsa_user_sgpr_queue_ptr 0
		.amdhsa_user_sgpr_kernarg_segment_ptr 1
		.amdhsa_user_sgpr_dispatch_id 0
		.amdhsa_user_sgpr_kernarg_preload_length 0
		.amdhsa_user_sgpr_kernarg_preload_offset 0
		.amdhsa_user_sgpr_private_segment_size 0
		.amdhsa_uses_dynamic_stack 0
		.amdhsa_enable_private_segment 0
		.amdhsa_system_sgpr_workgroup_id_x 1
		.amdhsa_system_sgpr_workgroup_id_y 0
		.amdhsa_system_sgpr_workgroup_id_z 0
		.amdhsa_system_sgpr_workgroup_info 0
		.amdhsa_system_vgpr_workitem_id 2
		.amdhsa_next_free_vgpr 256
		.amdhsa_next_free_sgpr 100
		.amdhsa_accum_offset 256
		.amdhsa_reserve_vcc 1
		.amdhsa_float_round_mode_32 0
		.amdhsa_float_round_mode_16_64 0
		.amdhsa_float_denorm_mode_32 3
		.amdhsa_float_denorm_mode_16_64 3
		.amdhsa_dx10_clamp 1
		.amdhsa_ieee_mode 1
		.amdhsa_fp16_overflow 0
		.amdhsa_tg_split 0
		.amdhsa_exception_fp_ieee_invalid_op 0
		.amdhsa_exception_fp_denorm_src 0
		.amdhsa_exception_fp_ieee_div_zero 0
		.amdhsa_exception_fp_ieee_overflow 0
		.amdhsa_exception_fp_ieee_underflow 0
		.amdhsa_exception_fp_ieee_inexact 0
		.amdhsa_exception_int_div_zero 0
	.end_amdhsa_kernel

; #define LAS __attribute__((address_space(3)))
; __global__ void __launch_bounds__(512, 2) fwd_megakernel(Args a) {
;     extern __shared__ __attribute__((aligned(16))) unsigned char shm[];
;     LAS unsigned char* lds = (LAS unsigned char*)shm;
;     const int tid = threadIdx.x, lane = tid & 63, wave = __builtin_amdgcn_readfirstlane(tid >> 6);
.Lfunc_end0:
	.size	_Z14fwd_megakernel4Args, .Lfunc_end0-_Z14fwd_megakernel4Args
	.set _Z14fwd_megakernel4Args.num_vgpr, 256
	.set _Z14fwd_megakernel4Args.num_agpr, 0
	.set _Z14fwd_megakernel4Args.numbered_sgpr, 100
	.set _Z14fwd_megakernel4Args.num_named_barrier, 0
	.set _Z14fwd_megakernel4Args.private_seg_size, 0
	.set _Z14fwd_megakernel4Args.uses_vcc, 1
	.set _Z14fwd_megakernel4Args.uses_flat_scratch, 0
	.set _Z14fwd_megakernel4Args.has_dyn_sized_stack, 0
	.set _Z14fwd_megakernel4Args.has_recursion, 0
	.set _Z14fwd_megakernel4Args.has_indirect_call, 0

; #define LAS __attribute__((address_space(3)))
; __global__ void __launch_bounds__(512, 2) fwd_megakernel(Args a) {
;     extern __shared__ __attribute__((aligned(16))) unsigned char shm[];
;     LAS unsigned char* lds = (LAS unsigned char*)shm;
;     const int tid = threadIdx.x, lane = tid & 63, wave = __builtin_amdgcn_readfirstlane(tid >> 6);
amdhsa.kernels:
  - .agpr_count:     0
    .args:
      - .offset:         0
        .size:           144
        .value_kind:     by_value
      - .offset:         144
        .size:           4
        .value_kind:     hidden_block_count_x
      - .offset:         148
        .size:           4
        .value_kind:     hidden_block_count_y
      - .offset:         152
        .size:           4
        .value_kind:     hidden_block_count_z
      - .offset:         156
        .size:           2
        .value_kind:     hidden_group_size_x
      - .offset:         158
        .size:           2
        .value_kind:     hidden_group_size_y
      - .offset:         160
        .size:           2
        .value_kind:     hidden_group_size_z
      - .offset:         162
        .size:           2
        .value_kind:     hidden_remainder_x
      - .offset:         164
        .size:           2
        .value_kind:     hidden_remainder_y
      - .offset:         166
        .size:           2
        .value_kind:     hidden_remainder_z
      - .offset:         184
        .size:           8
        .value_kind:     hidden_global_offset_x
      - .offset:         192
        .size:           8
        .value_kind:     hidden_global_offset_y
      - .offset:         200
        .size:           8
        .value_kind:     hidden_global_offset_z
      - .offset:         208
        .size:           2
        .value_kind:     hidden_grid_dims
      - .offset:         232
        .size:           8
        .value_kind:     hidden_multigrid_sync_arg
      - .offset:         264
        .size:           4
        .value_kind:     hidden_dynamic_lds_size
    .group_segment_fixed_size: 0
    .kernarg_segment_align: 8
    .kernarg_segment_size: 400
    .language:       OpenCL C
    .language_version:
      - 2
      - 0
    .max_flat_workgroup_size: 512
    .name:           _Z14fwd_megakernel4Args
    .private_segment_fixed_size: 0
    .sgpr_count:     106
    .sgpr_spill_count: 4
    .symbol:         _Z14fwd_megakernel4Args.kd
    .uniform_work_group_size: 1
    .uses_dynamic_stack: false
    .vgpr_count:     256
    .vgpr_spill_count: 0
    .wavefront_size: 64
